# comb20 + HGRN2 scan: LDS fragment reads of the S1/S2/S3a MFMA ladders issued together (counted waits) instead of read-wait-MFMA one at a time
# speedup vs baseline: 1.0080x; 1.0012x over previous
; #define LAS __attribute__((address_space(3)))
; __device__ __forceinline__ unsigned cvt_pk(float lo, float hi) { unsigned r; asm volatile("v_cvt_pk_bf16_f32 %0, %1, %2" : "=v"(r) : "v"(lo), "v"(hi)); return r; }
; __device__ __forceinline__ unsigned f2bf(float f) { unsigned u = __builtin_bit_cast(unsigned, f); return (u + 0x7fffu + ((u >> 16) & 1u)) >> 16; }
; __device__ __forceinline__ void scan_job(LAS unsigned char* lds, int b, int h, int dir, int layer, const bf16_t* P, const float* lbp, bf16_t* xc, bf16_t* ob) {
;     ...
;               for (int r = 0; r < 4; ++r) { const size_t row = dir ? row0 - r : row0 + r;
;                   if (dir == 0) xc[row * DM + 512 + col] = (bf16_t)f2bf(o[r]); else ob[row * 256 + col] = (bf16_t)f2bf(o[r]); } } }
;         { const f32x4 dec = *(const LAS f32x4*)(TOT + 16 * wid + 4 * lq);
;           const LAS unsigned char* ka = lds + S_K4T + (16 * wid + l15) * 144 + lq * 16; const bf16x8 k0 = *(const LAS bf16x8*)(ka), k1 = *(const LAS bf16x8*)(ka + 64);
; #pragma unroll
;           for (int vj = 0; vj < 4; ++vj) { const LAS unsigned char* vb = lds + S_VT + (16 * vj + l15) * 144 + lq * 16;
;               f32x4 a = Sacc[vj] * dec;
;               a = __builtin_amdgcn_mfma_f32_16x16x32_bf16(k0, *(const LAS bf16x8*)(vb), a, 0, 0, 0);
;               a = __builtin_amdgcn_mfma_f32_16x16x32_bf16(k1, *(const LAS bf16x8*)(vb + 64), a, 0, 0, 0);
;               Sacc[vj] = a; } }
;         __syncthreads();
; #pragma unroll
;         for (int vj = 0; vj < 4; ++vj) { u32x2 w; w.x = cvt_pk(Sacc[vj][0], Sacc[vj][1]); w.y = cvt_pk(Sacc[vj][2], Sacc[vj][3]);
;             *(LAS u32x2*)(lds + S_ST + (16 * vj + l15) * 272 + (16 * wid + 4 * lq) * 2) = w; }
.LBB0_622:
	v_lshl_add_u64 v[26:27], v[66:67], 0, s[72:73]
	v_bfe_u32 v22, v23, 16, 1
	v_add3_u32 v28, v23, v22, s92
	v_lshl_add_u64 v[22:23], v[26:27], 0, v[76:77]
	v_lshl_add_u64 v[26:27], v[22:23], 0, s[24:25]
	global_store_short_d16_hi v[26:27], v28, off offset:32
	v_bfe_u32 v26, v24, 16, 1
	v_add3_u32 v24, v24, v26, s92
	v_lshl_add_u64 v[26:27], v[22:23], 0, s[22:23]
	global_store_short_d16_hi v[26:27], v24, off offset:32
	v_bfe_u32 v24, v25, 16, 1
	v_add3_u32 v24, v25, v24, s92
	v_lshl_add_u64 v[22:23], v[22:23], 0, s[20:21]
	global_store_short_d16_hi v[22:23], v24, off offset:32
	ds_read_b128 v[22:25], v108
	ds_read_b128 v[26:29], v119
	ds_read_b128 v[30:33], v119 offset:64
	ds_read_b128 v[34:37], v120
	s_cmp_lg_u32 s97, 36
	s_waitcnt lgkmcnt(3)
	v_pk_mul_f32 v[8:9], v[8:9], v[24:25]
	v_pk_mul_f32 v[6:7], v[6:7], v[22:23]
	v_pk_mul_f32 v[12:13], v[12:13], v[24:25]
	v_pk_mul_f32 v[10:11], v[10:11], v[22:23]
	v_pk_mul_f32 v[16:17], v[16:17], v[24:25]
	v_pk_mul_f32 v[14:15], v[14:15], v[22:23]
	v_pk_mul_f32 v[20:21], v[20:21], v[24:25]
	v_pk_mul_f32 v[18:19], v[18:19], v[22:23]
	ds_read_b128 v[22:25], v120 offset:6912
	ds_read_b128 v[200:203], v120 offset:64
	ds_read_b128 v[204:207], v120 offset:6976
	ds_read_b128 v[208:211], v120 offset:2304
	ds_read_b128 v[212:215], v120 offset:2368
	ds_read_b128 v[216:219], v120 offset:4608
	ds_read_b128 v[220:223], v120 offset:4672
	s_waitcnt lgkmcnt(7)
	v_mfma_f32_16x16x32_bf16 v[6:9], v[26:29], v[34:37], v[6:9]
	s_waitcnt vmcnt(23)
	v_mov_b32_e32 v47, v122
	s_waitcnt vmcnt(21)
	v_mov_b32_e32 v44, v123
	s_waitcnt lgkmcnt(6)
	v_mfma_f32_16x16x32_bf16 v[18:21], v[26:29], v[22:25], v[18:21]
	s_waitcnt vmcnt(19)
	v_mov_b32_e32 v43, v124
	s_waitcnt vmcnt(17)
	v_mov_b32_e32 v42, v125
	s_waitcnt lgkmcnt(5)
	v_mfma_f32_16x16x32_bf16 v[6:9], v[30:33], v[200:203], v[6:9]
	s_waitcnt vmcnt(15)
	v_mov_b32_e32 v41, v126
	s_waitcnt vmcnt(13)
	v_mov_b32_e32 v40, v127
	s_waitcnt lgkmcnt(3)
	v_mfma_f32_16x16x32_bf16 v[10:13], v[26:29], v[208:211], v[10:13]
	s_waitcnt vmcnt(11)
	v_mov_b32_e32 v39, v128
	s_waitcnt vmcnt(9)
	v_mov_b32_e32 v38, v129
	s_waitcnt lgkmcnt(2)
	v_mfma_f32_16x16x32_bf16 v[10:13], v[30:33], v[212:215], v[10:13]
	s_mov_b32 s72, s97
	s_waitcnt lgkmcnt(1)
	v_mfma_f32_16x16x32_bf16 v[14:17], v[26:29], v[216:219], v[14:17]
	s_waitcnt lgkmcnt(0)
	s_barrier
	v_mfma_f32_16x16x32_bf16 v[14:17], v[30:33], v[220:223], v[14:17]
	v_mfma_f32_16x16x32_bf16 v[18:21], v[30:33], v[204:207], v[18:21]
	v_cvt_pk_bf16_f32 v22, v6, v7
	v_cvt_pk_bf16_f32 v23, v8, v9
	ds_write_b64 v121, v[22:23]
	v_cvt_pk_bf16_f32 v22, v10, v11
	v_cvt_pk_bf16_f32 v23, v12, v13
	ds_write_b64 v121, v[22:23] offset:4352
	v_cvt_pk_bf16_f32 v22, v14, v15
	v_cvt_pk_bf16_f32 v23, v16, v17
	ds_write_b64 v121, v[22:23] offset:8704
	v_cvt_pk_bf16_f32 v22, v18, v19
	v_cvt_pk_bf16_f32 v23, v20, v21
	ds_write_b64 v121, v[22:23] offset:13056
	s_cbranch_scc0 .LBB0_602

; #define LAS __attribute__((address_space(3)))
; __device__ __forceinline__ unsigned f2bf(float f) { unsigned u = __builtin_bit_cast(unsigned, f); return (u + 0x7fffu + ((u >> 16) & 1u)) >> 16; }
; __device__ __forceinline__ void scan_job(LAS unsigned char* lds, int b, int h, int dir, int layer, const bf16_t* P, const float* lbp, bf16_t* xc, bf16_t* ob) {
;     ...
;         for (int bl = wid; bl < 10; bl += 8) { const int bi = bl >= 6 ? 3 : (bl >= 3 ? 2 : (bl >= 1 ? 1 : 0)), bj = bl - (bi * (bi + 1)) / 2;
;             const LAS unsigned char* ap = lds + S_QT + (16 * bi + l15) * 272 + lq * 16;
;             const int krow = bi == bj ? 16 * bi : (bi == 1 ? 0 : (bi == 2 ? 16 : 48)) + 16 * bj;
;             const LAS unsigned char* bp = lds + (bi == bj ? S_KD : S_KX) + (krow + l15) * 272 + lq * 16;
;             f32x4 sc = (f32x4){0.f, 0.f, 0.f, 0.f};
; #pragma unroll
;             for (int ks = 0; ks < 4; ++ks) sc = __builtin_amdgcn_mfma_f32_16x16x32_bf16(*(const LAS bf16x8*)(ap + ks * 64), *(const LAS bf16x8*)(bp + ks * 64), sc, 0, 0, 0);
;             LAS bf16_t* pp = (LAS bf16_t*)(lds + S_P) + (16 * bi + 4 * lq) * 72 + 16 * bj + l15;
; #pragma unroll
;             for (int r = 0; r < 4; ++r) { float v = sc[r]; if (bi == bj && l15 > 4 * lq + r) v = 0.f; pp[r * 72] = (bf16_t)f2bf(v); } }
.LBB0_664:
	s_cmp_gt_i32 s23, 0
	s_cselect_b64 s[20:21], -1, 0
	v_cndmask_b32_e64 v23, 0, 1, s[20:21]
	s_cmp_lt_i32 s23, 3
	v_readfirstlane_b32 s20, v23
	s_cselect_b32 s20, s20, 2
	s_cmp_lt_i32 s23, 6
	s_cselect_b32 s20, s20, 3
	s_add_i32 s21, s20, 1
	s_mul_i32 s21, s21, s20
	s_lshr_b32 s24, s21, 1
	s_sub_i32 s21, s23, s24
	s_lshl_b32 s25, s20, 4
	s_add_i32 s33, s23, -3
	s_cmp_lt_u32 s33, 3
	s_cselect_b32 s33, 16, 48
	s_cmp_lg_u32 s20, 1
	s_cselect_b32 s33, s33, 0
	s_lshl_b32 s38, s24, 4
	s_sub_i32 s33, s33, s38
	s_add_i32 s33, s22, s33
	s_cmp_eq_u32 s21, s20
	s_cselect_b64 s[20:21], -1, 0
	s_and_b64 s[38:39], s[20:21], exec
	s_cselect_b32 s33, s25, s33
	v_or_b32_e32 v23, s25, v96
	s_cselect_b32 s38, s91, 0xcc00
	v_or_b32_e32 v24, s33, v96
	v_mad_u32_u24 v23, v23, s88, v105
	s_add_i32 s38, s38, 0
	v_mul_lo_u32 v24, v24, s88
	v_add3_u32 v36, s38, v24, v104
	ds_read_b128 v[24:27], v23
	ds_read_b128 v[28:31], v36
	ds_read_b128 v[200:203], v23 offset:64
	ds_read_b128 v[204:207], v36 offset:64
	ds_read_b128 v[208:211], v23 offset:128
	ds_read_b128 v[212:215], v36 offset:128
	ds_read_b128 v[216:219], v23 offset:192
	ds_read_b128 v[220:223], v36 offset:192
	s_waitcnt lgkmcnt(6)
	v_mfma_f32_16x16x32_bf16 v[24:27], v[24:27], v[28:31], 0
	s_lshl_b32 s24, s24, 5
	s_addk_i32 s22, 0x80
	s_waitcnt lgkmcnt(4)
	v_mfma_f32_16x16x32_bf16 v[24:27], v[200:203], v[204:207], v[24:27]
	s_waitcnt lgkmcnt(2)
	v_mfma_f32_16x16x32_bf16 v[24:27], v[208:211], v[212:215], v[24:27]
	v_or_b32_e32 v23, s25, v106
	v_mul_u32_u24_e32 v23, 0x90, v23
	s_waitcnt lgkmcnt(0)
	v_mfma_f32_16x16x32_bf16 v[24:27], v[216:219], v[220:223], v[24:27]
	v_subrev_u32_e32 v23, s24, v23
	s_and_b64 s[24:25], s[20:21], s[12:13]
	v_add_u32_e32 v23, v22, v23
	s_nop 4
	v_cndmask_b32_e64 v24, v24, 0, s[24:25]
	v_bfe_u32 v28, v24, 16, 1
	v_add3_u32 v24, v24, v28, s92
	s_and_b64 s[24:25], s[20:21], s[14:15]
	ds_write_b16_d16_hi v23, v24
	v_cndmask_b32_e64 v24, v25, 0, s[24:25]
	v_bfe_u32 v25, v24, 16, 1
	v_add3_u32 v24, v24, v25, s92
	s_and_b64 s[24:25], s[20:21], s[16:17]
	ds_write_b16_d16_hi v23, v24 offset:144
	v_cndmask_b32_e64 v24, v26, 0, s[24:25]
	v_bfe_u32 v25, v24, 16, 1
	v_add3_u32 v24, v24, v25, s92
	s_and_b64 s[20:21], s[20:21], s[18:19]
	ds_write_b16_d16_hi v23, v24 offset:288
	v_cndmask_b32_e64 v24, v27, 0, s[20:21]
	v_bfe_u32 v25, v24, 16, 1
	s_add_i32 s20, s23, 8
	v_add3_u32 v24, v24, v25, s92
	v_add_u32_e32 v22, 0x100, v22
	s_cmp_gt_i32 s23, 1
	s_mov_b32 s23, s20
	ds_write_b16_d16_hi v23, v24 offset:432
	s_cbranch_scc0 .LBB0_664

; #define LAS __attribute__((address_space(3)))
; __device__ __forceinline__ unsigned f2bf(float f) { unsigned u = __builtin_bit_cast(unsigned, f); return (u + 0x7fffu + ((u >> 16) & 1u)) >> 16; }
; __device__ __forceinline__ void scan_job(LAS unsigned char* lds, int b, int h, int dir, int layer, const bf16_t* P, const float* lbp, bf16_t* xc, bf16_t* ob) {
;     ...
;           for (int vv = 0; vv < 2; ++vv) { const int vj = vj0 + vv;
;               const LAS unsigned char* vb = lds + S_VT + (16 * vj + l15) * 144 + lq * 16; const LAS unsigned char* sb = lds + S_ST + (16 * vj + l15) * 272 + lq * 16;
;               f32x4 o = (f32x4){0.f, 0.f, 0.f, 0.f};
;               o = __builtin_amdgcn_mfma_f32_16x16x32_bf16(a0, *(const LAS bf16x8*)(vb), o, 0, 0, 0);
;               o = __builtin_amdgcn_mfma_f32_16x16x32_bf16(a1, *(const LAS bf16x8*)(vb + 64), o, 0, 0, 0);
;               o = __builtin_amdgcn_mfma_f32_16x16x32_bf16(q0, *(const LAS bf16x8*)(sb), o, 0, 0, 0);
;               o = __builtin_amdgcn_mfma_f32_16x16x32_bf16(q1, *(const LAS bf16x8*)(sb + 64), o, 0, 0, 0);
;               o = __builtin_amdgcn_mfma_f32_16x16x32_bf16(q2, *(const LAS bf16x8*)(sb + 128), o, 0, 0, 0);
;               o = __builtin_amdgcn_mfma_f32_16x16x32_bf16(q3, *(const LAS bf16x8*)(sb + 192), o, 0, 0, 0);
;               const int col = h * 64 + 16 * vj + l15;
; #pragma unroll
;               for (int r = 0; r < 4; ++r) { const size_t row = dir ? row0 - r : row0 + r;
;                   if (dir == 0) xc[row * DM + 512 + col] = (bf16_t)f2bf(o[r]); else ob[row * 256 + col] = (bf16_t)f2bf(o[r]); } } }
.LBB0_670:
	v_lshl_add_u64 v[82:83], v[64:65], 0, s[72:73]
	v_bfe_u32 v46, v47, 16, 1
	v_add3_u32 v130, v47, v46, s92
	v_lshl_add_u64 v[46:47], v[82:83], 0, v[80:81]
	v_lshl_add_u64 v[80:81], v[46:47], 0, s[24:25]
	global_store_short_d16_hi v[80:81], v130, off
	v_bfe_u32 v80, v48, 16, 1
	v_add3_u32 v48, v48, v80, s92
	v_lshl_add_u64 v[80:81], v[46:47], 0, s[22:23]
	global_store_short_d16_hi v[80:81], v48, off
	v_bfe_u32 v48, v49, 16, 1
	v_add3_u32 v48, v49, v48, s92
	v_lshl_add_u64 v[46:47], v[46:47], 0, s[20:21]
	global_store_short_d16_hi v[46:47], v48, off
	ds_read_b128 v[46:49], v117
	ds_read_b128 v[200:203], v117 offset:64
	ds_read_b128 v[204:207], v118
	ds_read_b128 v[208:211], v118 offset:64
	ds_read_b128 v[212:215], v118 offset:128
	ds_read_b128 v[216:219], v118 offset:192
	s_waitcnt lgkmcnt(5)
	v_mfma_f32_16x16x32_bf16 v[38:41], v[38:41], v[46:49], 0
	s_mov_b64 s[20:21], -1
	s_andn2_b64 vcc, exec, s[54:55]
	s_waitcnt lgkmcnt(4)
	v_mfma_f32_16x16x32_bf16 v[38:41], v[42:45], v[200:203], v[38:41]
	s_waitcnt lgkmcnt(3)
	v_mfma_f32_16x16x32_bf16 v[34:37], v[34:37], v[204:207], v[38:41]
	s_nop 4
	s_waitcnt lgkmcnt(2)
	v_mfma_f32_16x16x32_bf16 v[30:33], v[30:33], v[208:211], v[34:37]
	s_nop 2
	s_waitcnt lgkmcnt(1)
	v_mfma_f32_16x16x32_bf16 v[26:29], v[26:29], v[212:215], v[30:33]
	s_nop 2
	s_waitcnt lgkmcnt(0)
	v_mfma_f32_16x16x32_bf16 v[22:25], v[22:25], v[216:219], v[26:29]
	s_nop 7
	v_bfe_u32 v26, v22, 16, 1
	v_add3_u32 v22, v22, v26, s92
	v_lshrrev_b32_e32 v22, 16, v22
	s_cbranch_vccnz .LBB0_672
	v_lshl_add_u64 v[26:27], v[70:71], 0, v[76:77]
	s_mov_b64 s[20:21], 0
	global_store_short v[26:27], v22, off

; #define LAS __attribute__((address_space(3)))
; __device__ __forceinline__ unsigned cvt_pk(float lo, float hi) { unsigned r; asm volatile("v_cvt_pk_bf16_f32 %0, %1, %2" : "=v"(r) : "v"(lo), "v"(hi)); return r; }
; __device__ __forceinline__ unsigned f2bf(float f) { unsigned u = __builtin_bit_cast(unsigned, f); return (u + 0x7fffu + ((u >> 16) & 1u)) >> 16; }
; __device__ __forceinline__ void scan_job(LAS unsigned char* lds, int b, int h, int dir, int layer, const bf16_t* P, const float* lbp, bf16_t* xc, bf16_t* ob) {
;     ...
;               for (int r = 0; r < 4; ++r) { const size_t row = dir ? row0 - r : row0 + r;
;                   if (dir == 0) xc[row * DM + 512 + col] = (bf16_t)f2bf(o[r]); else ob[row * 256 + col] = (bf16_t)f2bf(o[r]); } } }
;         { const f32x4 dec = *(const LAS f32x4*)(TOT + 16 * wid + 4 * lq);
;           const LAS unsigned char* ka = lds + S_K4T + (16 * wid + l15) * 144 + lq * 16; const bf16x8 k0 = *(const LAS bf16x8*)(ka), k1 = *(const LAS bf16x8*)(ka + 64);
; #pragma unroll
;           for (int vj = 0; vj < 4; ++vj) { const LAS unsigned char* vb = lds + S_VT + (16 * vj + l15) * 144 + lq * 16;
;               f32x4 a = Sacc[vj] * dec;
;               a = __builtin_amdgcn_mfma_f32_16x16x32_bf16(k0, *(const LAS bf16x8*)(vb), a, 0, 0, 0);
;               a = __builtin_amdgcn_mfma_f32_16x16x32_bf16(k1, *(const LAS bf16x8*)(vb + 64), a, 0, 0, 0);
;               Sacc[vj] = a; } }
;         __syncthreads();
; #pragma unroll
;         for (int vj = 0; vj < 4; ++vj) { u32x2 w; w.x = cvt_pk(Sacc[vj][0], Sacc[vj][1]); w.y = cvt_pk(Sacc[vj][2], Sacc[vj][3]);
;             *(LAS u32x2*)(lds + S_ST + (16 * vj + l15) * 272 + (16 * wid + 4 * lq) * 2) = w; }
.LBB0_1682:
	v_lshl_add_u64 v[34:35], v[68:69], 0, s[66:67]
	v_bfe_u32 v22, v23, 16, 1
	ds_read_b128 v[26:29], v107
	ds_read_b128 v[30:33], v118
	v_add3_u32 v48, v23, v22, s89
	v_lshl_add_u64 v[22:23], v[34:35], 0, v[76:77]
	ds_read_b128 v[34:37], v118 offset:64
	ds_read_b128 v[38:41], v119
	s_waitcnt lgkmcnt(3)
	v_pk_mul_f32 v[8:9], v[8:9], v[28:29]
	v_pk_mul_f32 v[6:7], v[6:7], v[26:27]
	ds_read_b128 v[42:45], v119 offset:64
	ds_read_b128 v[200:203], v119 offset:2304
	ds_read_b128 v[204:207], v119 offset:2368
	ds_read_b128 v[208:211], v119 offset:4608
	ds_read_b128 v[212:215], v119 offset:6976
	ds_read_b128 v[216:219], v119 offset:4672
	ds_read_b128 v[220:223], v119 offset:6912
	v_pk_mul_f32 v[16:17], v[16:17], v[28:29]
	s_waitcnt lgkmcnt(7)
	v_mfma_f32_16x16x32_bf16 v[6:9], v[30:33], v[38:41], v[6:9]
	v_pk_mul_f32 v[14:15], v[14:15], v[26:27]
	v_pk_mul_f32 v[20:21], v[20:21], v[28:29]
	s_waitcnt lgkmcnt(6)
	v_mfma_f32_16x16x32_bf16 v[6:9], v[34:37], v[42:45], v[6:9]
	v_pk_mul_f32 v[18:19], v[18:19], v[26:27]
	v_pk_mul_f32 v[12:13], v[12:13], v[28:29]
	s_waitcnt lgkmcnt(5)
	v_mfma_f32_16x16x32_bf16 v[14:17], v[30:33], v[200:203], v[14:17]
	v_pk_mul_f32 v[10:11], v[10:11], v[26:27]
	s_waitcnt lgkmcnt(4)
	v_mfma_f32_16x16x32_bf16 v[14:17], v[34:37], v[204:207], v[14:17]
	v_lshl_add_u64 v[46:47], v[22:23], 0, s[24:25]
	global_store_short_d16_hi v[46:47], v48, off offset:32
	s_waitcnt lgkmcnt(3)
	v_mfma_f32_16x16x32_bf16 v[18:21], v[30:33], v[208:211], v[18:21]
	v_bfe_u32 v46, v24, 16, 1
	v_add3_u32 v24, v24, v46, s89
	s_waitcnt lgkmcnt(0)
	v_mfma_f32_16x16x32_bf16 v[10:13], v[30:33], v[220:223], v[10:13]
	v_lshl_add_u64 v[46:47], v[22:23], 0, s[22:23]
	global_store_short_d16_hi v[46:47], v24, off offset:32
	v_bfe_u32 v24, v25, 16, 1
	v_mfma_f32_16x16x32_bf16 v[18:21], v[34:37], v[216:219], v[18:21]
	v_add3_u32 v24, v25, v24, s89
	v_lshl_add_u64 v[22:23], v[22:23], 0, s[20:21]
	global_store_short_d16_hi v[22:23], v24, off offset:32
	v_mfma_f32_16x16x32_bf16 v[10:13], v[34:37], v[212:215], v[10:13]
	s_barrier
	v_cvt_pk_bf16_f32 v22, v6, v7
	v_cvt_pk_bf16_f32 v23, v8, v9
	ds_write_b64 v120, v[22:23]
	v_cvt_pk_bf16_f32 v22, v14, v15
	v_cvt_pk_bf16_f32 v23, v16, v17
	ds_write_b64 v120, v[22:23] offset:4352
	v_cvt_pk_bf16_f32 v22, v18, v19
	v_cvt_pk_bf16_f32 v23, v20, v21
	s_cmp_lg_u32 s94, 36
	s_waitcnt vmcnt(23)
	v_mov_b32_e32 v47, v121
	s_waitcnt vmcnt(21)
	v_mov_b32_e32 v44, v122
	s_waitcnt vmcnt(19)
	v_mov_b32_e32 v43, v123
	s_waitcnt vmcnt(17)
	v_mov_b32_e32 v42, v124
	s_waitcnt vmcnt(15)
	v_mov_b32_e32 v41, v125
	s_waitcnt vmcnt(13)
	v_mov_b32_e32 v40, v126
	s_waitcnt vmcnt(11)
	v_mov_b32_e32 v39, v127
	s_waitcnt vmcnt(9)
	v_mov_b32_e32 v38, v128
	s_mov_b32 s66, s94
	ds_write_b64 v120, v[22:23] offset:8704
	v_cvt_pk_bf16_f32 v22, v10, v11
	v_cvt_pk_bf16_f32 v23, v12, v13
	ds_write_b64 v120, v[22:23] offset:13056
	s_cbranch_scc0 .LBB0_1662

; #define LAS __attribute__((address_space(3)))
; __device__ __forceinline__ unsigned f2bf(float f) { unsigned u = __builtin_bit_cast(unsigned, f); return (u + 0x7fffu + ((u >> 16) & 1u)) >> 16; }
; __device__ __forceinline__ void scan_job(LAS unsigned char* lds, int b, int h, int dir, int layer, const bf16_t* P, const float* lbp, bf16_t* xc, bf16_t* ob) {
;     ...
;         for (int bl = wid; bl < 10; bl += 8) { const int bi = bl >= 6 ? 3 : (bl >= 3 ? 2 : (bl >= 1 ? 1 : 0)), bj = bl - (bi * (bi + 1)) / 2;
;             const LAS unsigned char* ap = lds + S_QT + (16 * bi + l15) * 272 + lq * 16;
;             const int krow = bi == bj ? 16 * bi : (bi == 1 ? 0 : (bi == 2 ? 16 : 48)) + 16 * bj;
;             const LAS unsigned char* bp = lds + (bi == bj ? S_KD : S_KX) + (krow + l15) * 272 + lq * 16;
;             f32x4 sc = (f32x4){0.f, 0.f, 0.f, 0.f};
; #pragma unroll
;             for (int ks = 0; ks < 4; ++ks) sc = __builtin_amdgcn_mfma_f32_16x16x32_bf16(*(const LAS bf16x8*)(ap + ks * 64), *(const LAS bf16x8*)(bp + ks * 64), sc, 0, 0, 0);
;             LAS bf16_t* pp = (LAS bf16_t*)(lds + S_P) + (16 * bi + 4 * lq) * 72 + 16 * bj + l15;
; #pragma unroll
;             for (int r = 0; r < 4; ++r) { float v = sc[r]; if (bi == bj && l15 > 4 * lq + r) v = 0.f; pp[r * 72] = (bf16_t)f2bf(v); } }
.LBB0_1724:
	s_cmp_gt_i32 s23, 0
	s_cselect_b64 s[20:21], -1, 0
	v_cndmask_b32_e64 v23, 0, 1, s[20:21]
	s_cmp_lt_i32 s23, 3
	v_readfirstlane_b32 s20, v23
	s_cselect_b32 s20, s20, 2
	s_cmp_lt_i32 s23, 6
	s_cselect_b32 s20, s20, 3
	s_add_i32 s21, s20, 1
	s_mul_i32 s21, s21, s20
	s_lshr_b32 s24, s21, 1
	s_sub_i32 s21, s23, s24
	s_lshl_b32 s25, s20, 4
	s_add_i32 s33, s23, -3
	s_cmp_lt_u32 s33, 3
	s_cselect_b32 s33, 16, 48
	s_cmp_lg_u32 s20, 1
	s_cselect_b32 s33, s33, 0
	s_lshl_b32 s62, s24, 4
	s_sub_i32 s33, s33, s62
	s_add_i32 s33, s22, s33
	s_cmp_eq_u32 s21, s20
	s_cselect_b64 s[20:21], -1, 0
	s_and_b64 s[62:63], s[20:21], exec
	s_cselect_b32 s33, s25, s33
	v_or_b32_e32 v23, s25, v97
	s_cselect_b32 s62, s88, 0xcc00
	v_or_b32_e32 v24, s33, v97
	v_mad_u32_u24 v23, v23, s85, v104
	s_add_i32 s62, s62, 0
	v_mul_lo_u32 v24, v24, s85
	v_add3_u32 v36, s62, v24, v103
	ds_read_b128 v[24:27], v23
	ds_read_b128 v[28:31], v36
	ds_read_b128 v[200:203], v23 offset:64
	ds_read_b128 v[204:207], v36 offset:64
	ds_read_b128 v[208:211], v23 offset:128
	ds_read_b128 v[212:215], v36 offset:128
	ds_read_b128 v[216:219], v23 offset:192
	ds_read_b128 v[220:223], v36 offset:192
	s_waitcnt lgkmcnt(6)
	v_mfma_f32_16x16x32_bf16 v[24:27], v[24:27], v[28:31], 0
	s_lshl_b32 s24, s24, 5
	s_addk_i32 s22, 0x80
	s_waitcnt lgkmcnt(4)
	v_mfma_f32_16x16x32_bf16 v[24:27], v[200:203], v[204:207], v[24:27]
	s_waitcnt lgkmcnt(2)
	v_mfma_f32_16x16x32_bf16 v[24:27], v[208:211], v[212:215], v[24:27]
	v_or_b32_e32 v23, s25, v105
	v_mul_u32_u24_e32 v23, 0x90, v23
	s_waitcnt lgkmcnt(0)
	v_mfma_f32_16x16x32_bf16 v[24:27], v[216:219], v[220:223], v[24:27]
	v_subrev_u32_e32 v23, s24, v23
	s_and_b64 s[24:25], s[20:21], s[12:13]
	v_add_u32_e32 v23, v22, v23
	s_nop 4
	v_cndmask_b32_e64 v24, v24, 0, s[24:25]
	v_bfe_u32 v28, v24, 16, 1
	v_add3_u32 v24, v24, v28, s89
	s_and_b64 s[24:25], s[20:21], s[14:15]
	ds_write_b16_d16_hi v23, v24
	v_cndmask_b32_e64 v24, v25, 0, s[24:25]
	v_bfe_u32 v25, v24, 16, 1
	v_add3_u32 v24, v24, v25, s89
	s_and_b64 s[24:25], s[20:21], s[16:17]
	ds_write_b16_d16_hi v23, v24 offset:144
	v_cndmask_b32_e64 v24, v26, 0, s[24:25]
	v_bfe_u32 v25, v24, 16, 1
	v_add3_u32 v24, v24, v25, s89
	s_and_b64 s[20:21], s[20:21], s[18:19]
	ds_write_b16_d16_hi v23, v24 offset:288
	v_cndmask_b32_e64 v24, v27, 0, s[20:21]
	v_bfe_u32 v25, v24, 16, 1
	s_add_i32 s20, s23, 8
	v_add3_u32 v24, v24, v25, s89
	v_add_u32_e32 v22, 0x100, v22
	s_cmp_gt_i32 s23, 1
	s_mov_b32 s23, s20
	ds_write_b16_d16_hi v23, v24 offset:432
	s_cbranch_scc0 .LBB0_1724

; #define LAS __attribute__((address_space(3)))
; __device__ __forceinline__ unsigned f2bf(float f) { unsigned u = __builtin_bit_cast(unsigned, f); return (u + 0x7fffu + ((u >> 16) & 1u)) >> 16; }
; __device__ __forceinline__ void scan_job(LAS unsigned char* lds, int b, int h, int dir, int layer, const bf16_t* P, const float* lbp, bf16_t* xc, bf16_t* ob) {
;     ...
;           for (int vv = 0; vv < 2; ++vv) { const int vj = vj0 + vv;
;               const LAS unsigned char* vb = lds + S_VT + (16 * vj + l15) * 144 + lq * 16; const LAS unsigned char* sb = lds + S_ST + (16 * vj + l15) * 272 + lq * 16;
;               f32x4 o = (f32x4){0.f, 0.f, 0.f, 0.f};
;               o = __builtin_amdgcn_mfma_f32_16x16x32_bf16(a0, *(const LAS bf16x8*)(vb), o, 0, 0, 0);
;               o = __builtin_amdgcn_mfma_f32_16x16x32_bf16(a1, *(const LAS bf16x8*)(vb + 64), o, 0, 0, 0);
;               o = __builtin_amdgcn_mfma_f32_16x16x32_bf16(q0, *(const LAS bf16x8*)(sb), o, 0, 0, 0);
;               o = __builtin_amdgcn_mfma_f32_16x16x32_bf16(q1, *(const LAS bf16x8*)(sb + 64), o, 0, 0, 0);
;               o = __builtin_amdgcn_mfma_f32_16x16x32_bf16(q2, *(const LAS bf16x8*)(sb + 128), o, 0, 0, 0);
;               o = __builtin_amdgcn_mfma_f32_16x16x32_bf16(q3, *(const LAS bf16x8*)(sb + 192), o, 0, 0, 0);
;               const int col = h * 64 + 16 * vj + l15;
; #pragma unroll
;               for (int r = 0; r < 4; ++r) { const size_t row = dir ? row0 - r : row0 + r;
;                   if (dir == 0) xc[row * DM + 512 + col] = (bf16_t)f2bf(o[r]); else ob[row * 256 + col] = (bf16_t)f2bf(o[r]); } } }
.LBB0_1730:
	ds_read_b128 v[130:133], v116
	v_lshl_add_u64 v[82:83], v[66:67], 0, s[66:67]
	v_bfe_u32 v46, v47, 16, 1
	v_add3_u32 v129, v47, v46, s89
	v_lshl_add_u64 v[46:47], v[82:83], 0, v[80:81]
	ds_read_b128 v[80:83], v116 offset:64
	ds_read_b128 v[200:203], v117
	s_waitcnt lgkmcnt(2)
	v_mfma_f32_16x16x32_bf16 v[26:29], v[26:29], v[130:133], 0
	v_lshl_add_u64 v[130:131], v[46:47], 0, s[24:25]
	global_store_short_d16_hi v[130:131], v129, off
	s_waitcnt lgkmcnt(1)
	v_mfma_f32_16x16x32_bf16 v[26:29], v[42:45], v[80:83], v[26:29]
	v_bfe_u32 v42, v48, 16, 1
	v_add3_u32 v48, v48, v42, s89
	ds_read_b128 v[42:45], v117 offset:64
	s_waitcnt lgkmcnt(1)
	v_mfma_f32_16x16x32_bf16 v[26:29], v[38:41], v[200:203], v[26:29]
	ds_read_b128 v[38:41], v117 offset:128
	v_lshl_add_u64 v[80:81], v[46:47], 0, s[22:23]
	v_bfe_u32 v82, v49, 16, 1
	s_waitcnt lgkmcnt(1)
	v_mfma_f32_16x16x32_bf16 v[26:29], v[34:37], v[42:45], v[26:29]
	ds_read_b128 v[34:37], v117 offset:192
	v_lshl_add_u64 v[42:43], v[46:47], 0, s[20:21]
	s_andn2_b64 vcc, exec, s[46:47]
	s_waitcnt lgkmcnt(1)
	v_mfma_f32_16x16x32_bf16 v[26:29], v[30:33], v[38:41], v[26:29]
	s_mov_b64 s[20:21], -1
	v_add3_u32 v44, v49, v82, s89
	global_store_short_d16_hi v[80:81], v48, off
	global_store_short_d16_hi v[42:43], v44, off
	s_waitcnt lgkmcnt(0)
	v_mfma_f32_16x16x32_bf16 v[22:25], v[22:25], v[34:37], v[26:29]
	s_nop 7
	v_bfe_u32 v26, v22, 16, 1
	v_add3_u32 v22, v22, v26, s89
	v_lshrrev_b32_e32 v22, 16, v22
	s_cbranch_vccnz .LBB0_1732
	v_lshl_add_u64 v[26:27], v[72:73], 0, v[76:77]
	s_mov_b64 s[20:21], 0
	global_store_short v[26:27], v22, off
